# q_pe fragment buffer moved to v234-237 so all 8 first-block V transpose reads issue after QK^T MFMA 22; first P.V MFMA issued before the K/V global prefetch block
# baseline (speedup 1.0000x reference)
; #define MFMA32(a, b, c) __builtin_amdgcn_mfma_f32_32x32x16_bf16((a), (b), (c), 0, 0, 0)
; DI void a_finishSM(f32x16& p0, f32x16& p1, float alpha, float& l_reg, bf16x8& pa0, bf16x8& pa1, bf16x8& pa2, bf16x8& pa3) {
; #pragma unroll
;   for (int r = 0; r < 16; ++r) p1[r] = __builtin_amdgcn_exp2f(p1[r]);
;   float ps = 0;
; #pragma unroll
;   for (int r = 0; r < 16; ++r) ps += p0[r];
; #pragma unroll
;   for (int r = 0; r < 16; ++r) ps += p1[r];
;   { auto rr = __builtin_amdgcn_permlane32_swap(__float_as_uint(ps), __float_as_uint(ps), false, false);
;     ps = __uint_as_float(rr[0]) + __uint_as_float(rr[1]); }
;   l_reg = l_reg * alpha + ps;
;     ...
;   PK4(p0, 0, pa0); PK4(p0, 8, pa1); PK4(p1, 0, pa2); PK4(p1, 8, pa3);
;     ...
; }
; DI void a_qkt(f32x16& p0, f32x16& p1, const char* Ks, const char* Ps, const bf16x8* qr, const char* QP, int r32, int hi) {
;   p0 = f32x16{}; p1 = f32x16{};
; #pragma unroll
;   for (int d0 = 0; d0 < 8; ++d0) { const int cb = (d0 * 16 + hi * 8) * 2;
;     bf16x8 b0 = *reinterpret_cast<const bf16x8*>(Ks + KSWZ(r32, cb));
;     bf16x8 b1 = *reinterpret_cast<const bf16x8*>(Ks + KSWZ(32 + r32, cb));
;     p0 = MFMA32(b0, qr[d0], p0);
;     p1 = MFMA32(b1, qr[d0], p1); }
; #pragma unroll
;   for (int d0 = 0; d0 < 4; ++d0) { const int cb = (d0 * 16 + hi * 8) * 2;
;     bf16x8 b0 = *reinterpret_cast<const bf16x8*>(Ps + PSWZ(r32, cb));
;     bf16x8 b1 = *reinterpret_cast<const bf16x8*>(Ps + PSWZ(32 + r32, cb));
;     const bf16x8 qp = *reinterpret_cast<const bf16x8*>(QP + d0 * 1024);
;     p0 = MFMA32(b0, qp, p0);
;     p1 = MFMA32(b1, qp, p1); }
; }
; template <int D0> DI void pv_one(f32x16& od, int vb, bf16x8 pa0, bf16x8 pa1, bf16x8 pa2, bf16x8 pa3) {
;   const s16x4 l0 = tr_read<v_rd_off(D0, 0, 0)>(vb), h0 = tr_read<v_rd_off(D0, 0, 1)>(vb), l1 = tr_read<v_rd_off(D0, 1, 0)>(vb), h1 = tr_read<v_rd_off(D0, 1, 1)>(vb);
;   const s16x4 l2 = tr_read<v_rd_off(D0, 2, 0)>(vb), h2 = tr_read<v_rd_off(D0, 2, 1)>(vb), l3 = tr_read<v_rd_off(D0, 3, 0)>(vb), h3 = tr_read<v_rd_off(D0, 3, 1)>(vb);
.LBB0_665:
	s_mov_b32 s8, s4
	s_add_i32 s4, s7, 0
	v_add_u32_e32 v70, s4, v170
	ds_read_b128 v[66:69], v70 offset:16384
	ds_read_b128 v[82:85], v70 offset:24576
	v_add_u32_e32 v166, s4, v172
	ds_read_b128 v[202:205], v166 offset:16384
	ds_read_b128 v[206:209], v166 offset:24576
	s_waitcnt lgkmcnt(3)
	v_mfma_f32_32x32x16_bf16 v[66:81], v[66:69], v[114:117], 0
	v_exp_f32_e32 v185, v130
	v_exp_f32_e32 v186, v131
	s_waitcnt lgkmcnt(2)
	v_mfma_f32_32x32x16_bf16 v[82:97], v[82:85], v[114:117], 0
	v_add_u32_e32 v166, s4, v173
	ds_read_b128 v[214:217], v166 offset:16384
	ds_read_b128 v[218:221], v166 offset:24576
	v_exp_f32_e32 v187, v146
	v_exp_f32_e32 v188, v147
	s_waitcnt lgkmcnt(3)
	v_mfma_f32_32x32x16_bf16 v[66:81], v[202:205], v[118:121], v[66:81]
	v_exp_f32_e32 v189, v132
	v_exp_f32_e32 v190, v133
	s_waitcnt lgkmcnt(2)
	v_mfma_f32_32x32x16_bf16 v[82:97], v[206:209], v[118:121], v[82:97]
	v_add_u32_e32 v166, s4, v174
	ds_read_b128 v[202:205], v166 offset:16384
	ds_read_b128 v[206:209], v166 offset:24576
	v_exp_f32_e32 v191, v148
	v_exp_f32_e32 v192, v149
	s_waitcnt lgkmcnt(3)
	v_mfma_f32_32x32x16_bf16 v[66:81], v[214:217], v[126:129], v[66:81]
	v_exp_f32_e32 v193, v150
	v_add_f32_e32 v201, 0, v240
	v_add_f32_e32 v201, v241, v201
	s_waitcnt lgkmcnt(2)
	v_mfma_f32_32x32x16_bf16 v[82:97], v[218:221], v[126:129], v[82:97]
	v_add_u32_e32 v166, s4, v175
	ds_read_b128 v[214:217], v166 offset:16384
	ds_read_b128 v[218:221], v166 offset:24576
	v_exp_f32_e32 v194, v151
	v_add_f32_e32 v201, v242, v201
	v_add_f32_e32 v201, v243, v201
	s_waitcnt lgkmcnt(3)
	v_mfma_f32_32x32x16_bf16 v[66:81], v[202:205], v[122:125], v[66:81]
	v_exp_f32_e32 v195, v154
	v_add_f32_e32 v201, v244, v201
	v_add_f32_e32 v201, v245, v201
	s_waitcnt lgkmcnt(2)
	v_mfma_f32_32x32x16_bf16 v[82:97], v[206:209], v[122:125], v[82:97]
	v_add_u32_e32 v166, s4, v176
	ds_read_b128 v[202:205], v166 offset:16384
	ds_read_b128 v[206:209], v166 offset:24576
	v_exp_f32_e32 v196, v155
	v_add_f32_e32 v201, v246, v201
	v_add_f32_e32 v201, v247, v201
	s_waitcnt lgkmcnt(3)
	v_mfma_f32_32x32x16_bf16 v[66:81], v[214:217], v[110:113], v[66:81]
	v_exp_f32_e32 v197, v152
	v_add_f32_e32 v201, v248, v201
	v_add_f32_e32 v201, v249, v201
	s_waitcnt lgkmcnt(2)
	v_mfma_f32_32x32x16_bf16 v[82:97], v[218:221], v[110:113], v[82:97]
	v_add_u32_e32 v166, s4, v177
	ds_read_b128 v[214:217], v166 offset:16384
	ds_read_b128 v[218:221], v166 offset:24576
	v_exp_f32_e32 v198, v153
	v_add_f32_e32 v201, v250, v201
	v_add_f32_e32 v201, v251, v201
	s_waitcnt lgkmcnt(3)
	v_mfma_f32_32x32x16_bf16 v[66:81], v[202:205], v[106:109], v[66:81]
	v_exp_f32_e32 v199, v156
	v_add_f32_e32 v201, v252, v201
	v_add_f32_e32 v201, v253, v201
	s_waitcnt lgkmcnt(2)
	v_mfma_f32_32x32x16_bf16 v[82:97], v[206:209], v[106:109], v[82:97]
	v_add_u32_e32 v166, s4, v178
	ds_read_b128 v[202:205], v166 offset:16384
	ds_read_b128 v[206:209], v166 offset:24576
	v_exp_f32_e32 v200, v157
	v_add_f32_e32 v201, v254, v201
	v_add_f32_e32 v201, v255, v201
	s_waitcnt lgkmcnt(3)
	v_mfma_f32_32x32x16_bf16 v[66:81], v[214:217], v[102:105], v[66:81]
	v_add_f32_e32 v201, v185, v201
	v_add_f32_e32 v201, v186, v201
	v_cvt_pk_bf16_f32 v130, v240, v241
	s_waitcnt lgkmcnt(2)
	v_mfma_f32_32x32x16_bf16 v[82:97], v[218:221], v[102:105], v[82:97]
	v_add_u32_e32 v166, s4, v179
	ds_read_b128 v[214:217], v166 offset:32768
	ds_read_b128 v[218:221], v166 offset:36864
	ds_read_b128 v[222:225], v163
	v_add_f32_e32 v201, v187, v201
	v_add_f32_e32 v201, v188, v201
	v_cvt_pk_bf16_f32 v131, v242, v243
	s_waitcnt lgkmcnt(4)
	v_mfma_f32_32x32x16_bf16 v[66:81], v[202:205], v[98:101], v[66:81]
	v_add_f32_e32 v201, v189, v201
	v_add_f32_e32 v201, v190, v201
	v_cvt_pk_bf16_f32 v132, v244, v245
	s_waitcnt lgkmcnt(3)
	v_mfma_f32_32x32x16_bf16 v[82:97], v[206:209], v[98:101], v[82:97]
	v_add_u32_e32 v166, s4, v180
	ds_read_b128 v[202:205], v166 offset:32768
	ds_read_b128 v[206:209], v166 offset:36864
	ds_read_b128 v[234:237], v163 offset:1024
	v_add_f32_e32 v201, v191, v201
	v_add_f32_e32 v201, v192, v201
	v_cvt_pk_bf16_f32 v133, v246, v247
	s_waitcnt lgkmcnt(3)
	v_mfma_f32_32x32x16_bf16 v[66:81], v[214:217], v[222:225], v[66:81]
	v_add_f32_e32 v201, v193, v201
	v_add_f32_e32 v201, v194, v201
	v_cvt_pk_bf16_f32 v154, v248, v249
	v_mfma_f32_32x32x16_bf16 v[82:97], v[218:221], v[222:225], v[82:97]
	v_add_u32_e32 v166, s4, v181
	ds_read_b128 v[214:217], v166 offset:32768
	ds_read_b128 v[218:221], v166 offset:36864
	ds_read_b128 v[222:225], v163 offset:2048
	v_add_f32_e32 v201, v195, v201
	v_add_f32_e32 v201, v196, v201
	v_cvt_pk_bf16_f32 v155, v250, v251
	s_waitcnt lgkmcnt(3)
	v_mfma_f32_32x32x16_bf16 v[66:81], v[202:205], v[234:237], v[66:81]
	v_add_f32_e32 v201, v197, v201
	v_add_f32_e32 v201, v198, v201
	v_cvt_pk_bf16_f32 v156, v252, v253
	v_mfma_f32_32x32x16_bf16 v[82:97], v[206:209], v[234:237], v[82:97]
	v_add_u32_e32 v166, s4, v182
	ds_read_b128 v[202:205], v166 offset:32768
	ds_read_b128 v[206:209], v166 offset:36864
	ds_read_b128 v[234:237], v163 offset:3072
	v_add_f32_e32 v201, v199, v201
	v_add_f32_e32 v150, v200, v201
	v_cvt_pk_bf16_f32 v157, v254, v255
	s_waitcnt lgkmcnt(3)
	v_mfma_f32_32x32x16_bf16 v[66:81], v[214:217], v[222:225], v[66:81]
	v_mov_b32_e32 v151, v150
	v_cvt_pk_bf16_f32 v184, v185, v186
	v_cvt_pk_bf16_f32 v185, v187, v188
	v_permlane32_swap_b32_e32 v130, v132
	v_mfma_f32_32x32x16_bf16 v[82:97], v[218:221], v[222:225], v[82:97]
	v_add_u32_e32 v166, s8, v171
	ds_read_b64_tr_b16 v[212:213], v166 offset:0
	ds_read_b64_tr_b16 v[214:215], v166 offset:2048
	ds_read_b64_tr_b16 v[216:217], v166 offset:4096
	ds_read_b64_tr_b16 v[218:219], v166 offset:6144
	ds_read_b64_tr_b16 v[220:221], v166 offset:8192
	ds_read_b64_tr_b16 v[222:223], v166 offset:10240
	ds_read_b64_tr_b16 v[224:225], v166 offset:12288
	ds_read_b64_tr_b16 v[226:227], v166 offset:14336
	v_cvt_pk_bf16_f32 v186, v189, v190
	v_cvt_pk_bf16_f32 v187, v191, v192
	v_permlane32_swap_b32_e32 v150, v151
	v_permlane32_swap_b32_e32 v131, v133
	s_waitcnt lgkmcnt(8)
; DI void pv_sm(f32x16* o, int vb, bf16x8 pa0, bf16x8 pa1, bf16x8 pa2, bf16x8 pa3, f32x16& p0, f32x16& p1, float& m_reg, float& mn, float& alpha) {
;   PV_BLOCK(0)
;   float pm0 = p0[0];
; #pragma unroll
;   for (int r = 1; r < 16; ++r) pm0 = fmaxf(pm0, p0[r]);
;   PV_BLOCK(1)
;   float pmax = pm0;
; #pragma unroll
;   for (int r = 0; r < 16; ++r) pmax = fmaxf(pmax, p1[r]);
;   { auto rr = __builtin_amdgcn_permlane32_swap(__float_as_uint(pmax), __float_as_uint(pmax), false, false);
;     pmax = fmaxf(__uint_as_float(rr[0]), __uint_as_float(rr[1])); }
;   const bool keep = __all(pmax - m_reg <= ATH);
;   mn = keep ? m_reg : fmaxf(m_reg, pmax);
;   alpha = __builtin_amdgcn_exp2f(m_reg - mn);
;   m_reg = mn;
;   PV_BLOCK(2)
; #pragma unroll
;   for (int r = 0; r < 16; ++r) { p0[r] = p0[r] - mn; p1[r] = p1[r] - mn; }
;   PV_BLOCK(3)
; #pragma unroll
;   for (int r = 0; r < 16; ++r) p0[r] = __builtin_amdgcn_exp2f(p0[r]);
; }
	v_mfma_f32_32x32x16_bf16 v[66:81], v[202:205], v[234:237], v[66:81]
	v_cvt_pk_bf16_f32 v188, v193, v194
	v_cvt_pk_bf16_f32 v189, v195, v196
	v_permlane32_swap_b32_e32 v154, v156
	v_mfma_f32_32x32x16_bf16 v[82:97], v[206:209], v[234:237], v[82:97]
	v_cvt_pk_bf16_f32 v190, v197, v198
	v_cvt_pk_bf16_f32 v191, v199, v200
	v_permlane32_swap_b32_e32 v155, v157
	s_nop 0
	v_permlane32_swap_b32_e32 v184, v186
	v_permlane32_swap_b32_e32 v185, v187
	v_permlane32_swap_b32_e32 v188, v190
	v_permlane32_swap_b32_e32 v189, v191
	s_waitcnt lgkmcnt(0)
	s_nop 0
	v_mfma_f32_32x32x16_bf16 v[2:17], v[130:133], v[212:215], v[2:17]
	v_lshl_add_u64 v[146:147], s[84:85], 0, v[142:143]
	v_add_co_u32_e32 v148, vcc, s56, v146
	s_nop 1
	v_addc_co_u32_e32 v149, vcc, 0, v147, vcc
	v_add_co_u32_e32 v152, vcc, s57, v146
	s_nop 1
	v_addc_co_u32_e32 v153, vcc, 0, v147, vcc
	global_load_dwordx4 v[192:195], v[148:149], off offset:256
	global_load_dwordx4 v[196:199], v[148:149], off
	global_load_dwordx4 v[200:203], v[152:153], off offset:256
	global_load_dwordx4 v[204:207], v[152:153], off
	v_lshl_add_u64 v[148:149], s[84:85], 0, v[140:141]
	v_add_co_u32_e32 v152, vcc, s58, v148
	s_nop 1
	v_addc_co_u32_e32 v153, vcc, 0, v149, vcc
	global_load_dwordx4 v[208:211], v[152:153], off
	v_add_u32_e32 v166, s8, v171
	ds_read_b64_tr_b16 v[212:213], v166 offset:0x200
	ds_read_b64_tr_b16 v[214:215], v166 offset:0xa00
	v_max_f32_e32 v152, v67, v67
	v_max_f32_e32 v153, v66, v66
	v_max_f32_e32 v152, v153, v152
	v_max3_f32 v152, v152, v68, v69
	v_max3_f32 v152, v152, v70, v71
	v_mfma_f32_32x32x16_bf16 v[2:17], v[154:157], v[216:219], v[2:17]
	ds_read_b64_tr_b16 v[216:217], v166 offset:0x1200
	ds_read_b64_tr_b16 v[218:219], v166 offset:0x1a00
	v_max3_f32 v152, v152, v72, v73
	v_max3_f32 v152, v152, v74, v75
	v_max3_f32 v152, v152, v76, v77
	v_max3_f32 v152, v152, v78, v79
	v_max3_f32 v152, v152, v80, v81
	v_mfma_f32_32x32x16_bf16 v[2:17], v[184:187], v[220:223], v[2:17]
	ds_read_b64_tr_b16 v[220:221], v166 offset:0x2200
	ds_read_b64_tr_b16 v[222:223], v166 offset:0x2a00
	ds_read_b64_tr_b16 v[228:229], v166 offset:0x3200
	ds_read_b64_tr_b16 v[230:231], v166 offset:0x3a00
	v_mfma_f32_32x32x16_bf16 v[2:17], v[188:191], v[224:227], v[2:17]
	s_waitcnt lgkmcnt(0)
	v_mfma_f32_32x32x16_bf16 v[50:65], v[130:133], v[212:215], v[50:65]
	v_max3_f32 v152, v152, v82, v83
	v_max3_f32 v152, v152, v84, v85
	v_max3_f32 v152, v152, v86, v87
	v_max3_f32 v152, v152, v88, v89
	v_max3_f32 v152, v152, v90, v91
	v_max3_f32 v152, v152, v92, v93
	v_max3_f32 v152, v152, v94, v95
	v_mfma_f32_32x32x16_bf16 v[50:65], v[154:157], v[216:219], v[50:65]
	v_max3_f32 v152, v152, v96, v97
	v_mov_b32_e32 v153, v152
	s_nop 1
	v_permlane32_swap_b32_e32 v152, v153
	v_max_f32_e32 v153, v153, v153
	v_max_f32_e32 v152, v152, v152
	v_max_f32_e32 v152, v152, v153
	v_mfma_f32_32x32x16_bf16 v[50:65], v[184:187], v[220:223], v[50:65]
	ds_read_b64_tr_b16 v[212:213], v166 offset:0x400
	v_sub_f32_e32 v153, v152, v144
	ds_read_b64_tr_b16 v[214:215], v166 offset:0xc00
	v_cmp_ge_f32_e32 vcc, s54, v153
	ds_read_b64_tr_b16 v[216:217], v166 offset:0x1400
	s_cmp_eq_u64 vcc, exec
	v_max_f32_e32 v153, v144, v144
	ds_read_b64_tr_b16 v[218:219], v166 offset:0x1c00
	ds_read_b64_tr_b16 v[220:221], v166 offset:0x2400
	ds_read_b64_tr_b16 v[222:223], v166 offset:0x2c00
	ds_read_b64_tr_b16 v[224:225], v166 offset:0x3400
	ds_read_b64_tr_b16 v[226:227], v166 offset:0x3c00
	v_mfma_f32_32x32x16_bf16 v[50:65], v[188:191], v[228:231], v[50:65]
	v_max_f32_e32 v152, v153, v152
	s_cselect_b64 vcc, -1, 0
	v_cndmask_b32_e32 v153, v152, v144, vcc
	v_sub_f32_e32 v144, v144, v153
	v_exp_f32_e32 v152, v144
	s_waitcnt lgkmcnt(0)
	v_mfma_f32_32x32x16_bf16 v[34:49], v[130:133], v[212:215], v[34:49]
	ds_read_b64_tr_b16 v[212:213], v166 offset:0x600
	ds_read_b64_tr_b16 v[214:215], v166 offset:0xe00
	v_sub_f32_e32 v66, v66, v153
	v_sub_f32_e32 v67, v67, v153
	v_sub_f32_e32 v68, v68, v153
	v_sub_f32_e32 v69, v69, v153
	v_mfma_f32_32x32x16_bf16 v[34:49], v[154:157], v[216:219], v[34:49]
	ds_read_b64_tr_b16 v[216:217], v166 offset:0x1600
	ds_read_b64_tr_b16 v[218:219], v166 offset:0x1e00
	v_sub_f32_e32 v70, v70, v153
	v_sub_f32_e32 v71, v71, v153
	v_exp_f32_e32 v240, v66
	v_exp_f32_e32 v241, v67
	v_mfma_f32_32x32x16_bf16 v[34:49], v[184:187], v[220:223], v[34:49]
	ds_read_b64_tr_b16 v[220:221], v166 offset:0x2600
	ds_read_b64_tr_b16 v[222:223], v166 offset:0x2e00
	ds_read_b64_tr_b16 v[228:229], v166 offset:0x3600
	ds_read_b64_tr_b16 v[230:231], v166 offset:0x3e00
	v_mfma_f32_32x32x16_bf16 v[34:49], v[188:191], v[224:227], v[34:49]
	v_sub_f32_e32 v72, v72, v153
	v_sub_f32_e32 v73, v73, v153
	v_exp_f32_e32 v242, v68
	v_exp_f32_e32 v243, v69
	s_waitcnt lgkmcnt(0)
	v_sub_f32_e32 v74, v74, v153
	v_sub_f32_e32 v75, v75, v153
	v_exp_f32_e32 v244, v70
	v_exp_f32_e32 v245, v71
	v_mfma_f32_32x32x16_bf16 v[18:33], v[130:133], v[212:215], v[18:33]
	v_sub_f32_e32 v76, v76, v153
	v_sub_f32_e32 v77, v77, v153
	v_exp_f32_e32 v246, v72
	v_exp_f32_e32 v247, v73
	s_add_i32 s9, s6, 0
	v_add_u32_e32 v130, s9, v164
	s_waitcnt vmcnt(0)
	s_waitcnt vmcnt(4)
	ds_write_b128 v130, v[192:195]
	v_add_u32_e32 v130, s9, v165
	s_waitcnt vmcnt(2)
	ds_write_b128 v130, v[200:203]
	v_add_u32_e32 v130, s9, v167
	v_mfma_f32_32x32x16_bf16 v[18:33], v[154:157], v[216:219], v[18:33]
	ds_write_b128 v130, v[196:199] offset:16384
	v_add_u32_e32 v130, s9, v168
	s_waitcnt vmcnt(1)
	ds_write_b128 v130, v[204:207] offset:16384
	v_add_u32_e32 v130, s9, v169
	v_cmp_gt_f32_e32 vcc, 1.0, v152
	s_waitcnt vmcnt(0)
	ds_write_b128 v130, v[208:211] offset:32768
	v_sub_f32_e32 v78, v78, v153
	v_sub_f32_e32 v79, v79, v153
	v_exp_f32_e32 v248, v74
	v_exp_f32_e32 v249, v75
	v_mfma_f32_32x32x16_bf16 v[18:33], v[184:187], v[220:223], v[18:33]
	v_sub_f32_e32 v80, v80, v153
	v_sub_f32_e32 v81, v81, v153
	v_exp_f32_e32 v250, v76
	v_exp_f32_e32 v251, v77
	v_mfma_f32_32x32x16_bf16 v[18:33], v[188:191], v[228:231], v[18:33]
	v_exp_f32_e32 v252, v78
	v_exp_f32_e32 v253, v79
	v_exp_f32_e32 v254, v80
	v_exp_f32_e32 v255, v81
	s_cbranch_vccz .LBB0_669
; #define MFMA32(a, b, c) __builtin_amdgcn_mfma_f32_32x32x16_bf16((a), (b), (c), 0, 0, 0)
; DI void a_finishSM(f32x16& p0, f32x16& p1, float alpha, float& l_reg, bf16x8& pa0, bf16x8& pa1, bf16x8& pa2, bf16x8& pa3) {
; #pragma unroll
;   for (int r = 0; r < 16; ++r) p1[r] = __builtin_amdgcn_exp2f(p1[r]);
;   float ps = 0;
; #pragma unroll
;   for (int r = 0; r < 16; ++r) ps += p0[r];
; #pragma unroll
;   for (int r = 0; r < 16; ++r) ps += p1[r];
;   { auto rr = __builtin_amdgcn_permlane32_swap(__float_as_uint(ps), __float_as_uint(ps), false, false);
;     ps = __uint_as_float(rr[0]) + __uint_as_float(rr[1]); }
;   l_reg = l_reg * alpha + ps;
;     ...
;   PK4(p0, 0, pa0); PK4(p0, 8, pa1); PK4(p1, 0, pa2); PK4(p1, 8, pa3);
;     ...
; }
; DI void a_qkt(f32x16& p0, f32x16& p1, const char* Ks, const char* Ps, const bf16x8* qr, const char* QP, int r32, int hi) {
;   p0 = f32x16{}; p1 = f32x16{};
; #pragma unroll
;   for (int d0 = 0; d0 < 8; ++d0) { const int cb = (d0 * 16 + hi * 8) * 2;
;     bf16x8 b0 = *reinterpret_cast<const bf16x8*>(Ks + KSWZ(r32, cb));
;     bf16x8 b1 = *reinterpret_cast<const bf16x8*>(Ks + KSWZ(32 + r32, cb));
;     p0 = MFMA32(b0, qr[d0], p0);
;     p1 = MFMA32(b1, qr[d0], p1); }
; #pragma unroll
;   for (int d0 = 0; d0 < 4; ++d0) { const int cb = (d0 * 16 + hi * 8) * 2;
;     bf16x8 b0 = *reinterpret_cast<const bf16x8*>(Ps + PSWZ(r32, cb));
;     bf16x8 b1 = *reinterpret_cast<const bf16x8*>(Ps + PSWZ(32 + r32, cb));
;     const bf16x8 qp = *reinterpret_cast<const bf16x8*>(QP + d0 * 1024);
;     p0 = MFMA32(b0, qp, p0);
;     p1 = MFMA32(b1, qp, p1); }
; }
	s_and_saveexec_b64 s[4:5], s[2:3]
	ds_write_b32 v161, v152 offset:128
	s_or_b64 exec, exec, s[4:5]
	s_waitcnt lgkmcnt(0)
	v_add_u32_e32 v144, v137, v134
	ds_read_b128 v[130:133], v144 offset:224
	ds_read_b128 v[154:157], v144 offset:192
	ds_read_b128 v[184:187], v144 offset:160
	ds_read_b128 v[188:191], v144 offset:128
	s_waitcnt lgkmcnt(3)
	v_pk_mul_f32 v[14:15], v[14:15], v[130:131]
	s_waitcnt lgkmcnt(2)
	v_pk_mul_f32 v[10:11], v[10:11], v[154:155]
	s_waitcnt lgkmcnt(1)
	v_pk_mul_f32 v[6:7], v[6:7], v[184:185]
	v_pk_mul_f32 v[16:17], v[16:17], v[132:133]
	v_pk_mul_f32 v[12:13], v[12:13], v[156:157]
	v_pk_mul_f32 v[8:9], v[8:9], v[186:187]
	s_waitcnt lgkmcnt(0)
	v_pk_mul_f32 v[4:5], v[4:5], v[190:191]
	v_pk_mul_f32 v[2:3], v[2:3], v[188:189]
	v_pk_mul_f32 v[62:63], v[62:63], v[130:131]
	v_pk_mul_f32 v[58:59], v[58:59], v[154:155]
	v_pk_mul_f32 v[54:55], v[54:55], v[184:185]
	v_pk_mul_f32 v[64:65], v[64:65], v[132:133]
	v_pk_mul_f32 v[60:61], v[60:61], v[156:157]
	v_pk_mul_f32 v[56:57], v[56:57], v[186:187]
	v_pk_mul_f32 v[52:53], v[52:53], v[190:191]
	v_pk_mul_f32 v[50:51], v[50:51], v[188:189]
	v_pk_mul_f32 v[46:47], v[46:47], v[130:131]
	v_pk_mul_f32 v[42:43], v[42:43], v[154:155]
	v_pk_mul_f32 v[38:39], v[38:39], v[184:185]
	v_pk_mul_f32 v[48:49], v[48:49], v[132:133]
	v_pk_mul_f32 v[44:45], v[44:45], v[156:157]
	v_pk_mul_f32 v[40:41], v[40:41], v[186:187]
	v_pk_mul_f32 v[36:37], v[36:37], v[190:191]
	v_pk_mul_f32 v[34:35], v[34:35], v[188:189]
	v_pk_mul_f32 v[30:31], v[30:31], v[130:131]
	v_pk_mul_f32 v[26:27], v[26:27], v[154:155]
	v_pk_mul_f32 v[22:23], v[22:23], v[184:185]
	v_pk_mul_f32 v[32:33], v[32:33], v[132:133]
	v_pk_mul_f32 v[28:29], v[28:29], v[156:157]
	v_pk_mul_f32 v[24:25], v[24:25], v[186:187]
	v_pk_mul_f32 v[20:21], v[20:21], v[190:191]
	v_pk_mul_f32 v[18:19], v[18:19], v[188:189]
.LBB0_669:
	s_waitcnt lgkmcnt(0)
	s_barrier
	v_add_u32_e32 v70, s9, v170
	ds_read_b128 v[66:69], v70 offset:16384
	ds_read_b128 v[70:73], v70 offset:24576
	v_add_u32_e32 v226, s9, v172
	ds_read_b128 v[204:207], v226 offset:16384
	ds_read_b128 v[208:211], v226 offset:24576
	v_sub_f32_e32 v144, v82, v153
	v_sub_f32_e32 v188, v83, v153
	v_sub_f32_e32 v189, v84, v153
	v_sub_f32_e32 v190, v85, v153
	v_sub_f32_e32 v191, v86, v153
	v_sub_f32_e32 v192, v87, v153
	v_sub_f32_e32 v193, v88, v153
	v_sub_f32_e32 v194, v89, v153
	v_sub_f32_e32 v195, v90, v153
	v_sub_f32_e32 v196, v91, v153
	v_sub_f32_e32 v197, v92, v153
	v_sub_f32_e32 v198, v93, v153
	v_sub_f32_e32 v199, v94, v153
	v_sub_f32_e32 v200, v95, v153
	v_sub_f32_e32 v201, v96, v153
	v_sub_f32_e32 v202, v97, v153
	s_waitcnt lgkmcnt(3)
	v_mfma_f32_32x32x16_bf16 v[82:97], v[66:69], v[114:117], 0
	v_exp_f32_e32 v144, v144
	v_exp_f32_e32 v156, v188
	s_waitcnt lgkmcnt(2)
	v_mfma_f32_32x32x16_bf16 v[66:81], v[70:73], v[114:117], 0
	v_add_u32_e32 v226, s9, v173
	ds_read_b128 v[216:219], v226 offset:16384
	ds_read_b128 v[220:223], v226 offset:24576
	v_exp_f32_e32 v157, v189
	v_exp_f32_e32 v184, v190
	s_waitcnt lgkmcnt(3)
	v_mfma_f32_32x32x16_bf16 v[82:97], v[204:207], v[118:121], v[82:97]
	v_exp_f32_e32 v185, v191
	v_exp_f32_e32 v192, v192
	s_waitcnt lgkmcnt(2)
	v_mfma_f32_32x32x16_bf16 v[66:81], v[208:211], v[118:121], v[66:81]
	v_add_u32_e32 v226, s9, v174
	ds_read_b128 v[204:207], v226 offset:16384
	ds_read_b128 v[208:211], v226 offset:24576
	v_exp_f32_e32 v193, v193
	v_exp_f32_e32 v194, v194
	s_waitcnt lgkmcnt(3)
	v_mfma_f32_32x32x16_bf16 v[82:97], v[216:219], v[126:129], v[82:97]
	v_exp_f32_e32 v195, v195
	v_add_f32_e32 v203, 0, v240
	v_add_f32_e32 v203, v241, v203
	s_waitcnt lgkmcnt(2)
	v_mfma_f32_32x32x16_bf16 v[66:81], v[220:223], v[126:129], v[66:81]
	v_add_u32_e32 v226, s9, v175
	ds_read_b128 v[216:219], v226 offset:16384
	ds_read_b128 v[220:223], v226 offset:24576
	v_exp_f32_e32 v196, v196
	v_add_f32_e32 v203, v242, v203
	v_add_f32_e32 v203, v243, v203
	s_waitcnt lgkmcnt(3)
	v_mfma_f32_32x32x16_bf16 v[82:97], v[204:207], v[122:125], v[82:97]
	v_exp_f32_e32 v197, v197
	v_add_f32_e32 v203, v244, v203
	v_add_f32_e32 v203, v245, v203
	s_waitcnt lgkmcnt(2)
	v_mfma_f32_32x32x16_bf16 v[66:81], v[208:211], v[122:125], v[66:81]
	v_add_u32_e32 v226, s9, v176
	ds_read_b128 v[204:207], v226 offset:16384
	ds_read_b128 v[208:211], v226 offset:24576
	v_exp_f32_e32 v198, v198
	v_add_f32_e32 v203, v246, v203
	v_add_f32_e32 v203, v247, v203
	s_waitcnt lgkmcnt(3)
	v_mfma_f32_32x32x16_bf16 v[82:97], v[216:219], v[110:113], v[82:97]
	v_exp_f32_e32 v199, v199
	v_add_f32_e32 v203, v248, v203
	v_add_f32_e32 v203, v249, v203
	s_waitcnt lgkmcnt(2)
	v_mfma_f32_32x32x16_bf16 v[66:81], v[220:223], v[110:113], v[66:81]
	v_add_u32_e32 v226, s9, v177
	ds_read_b128 v[216:219], v226 offset:16384
	ds_read_b128 v[220:223], v226 offset:24576
	v_exp_f32_e32 v200, v200
	v_add_f32_e32 v203, v250, v203
	v_add_f32_e32 v203, v251, v203
	s_waitcnt lgkmcnt(3)
	v_mfma_f32_32x32x16_bf16 v[82:97], v[204:207], v[106:109], v[82:97]
	v_exp_f32_e32 v201, v201
	v_add_f32_e32 v203, v252, v203
	v_add_f32_e32 v203, v253, v203
	s_waitcnt lgkmcnt(2)
	v_mfma_f32_32x32x16_bf16 v[66:81], v[208:211], v[106:109], v[66:81]
	v_add_u32_e32 v226, s9, v178
	ds_read_b128 v[204:207], v226 offset:16384
	ds_read_b128 v[208:211], v226 offset:24576
	v_exp_f32_e32 v202, v202
	v_add_f32_e32 v203, v254, v203
	v_add_f32_e32 v203, v255, v203
	s_waitcnt lgkmcnt(3)
	v_mfma_f32_32x32x16_bf16 v[82:97], v[216:219], v[102:105], v[82:97]
	v_add_f32_e32 v203, v144, v203
	v_add_f32_e32 v203, v156, v203
	v_cvt_pk_bf16_f32 v130, v240, v241
	s_waitcnt lgkmcnt(2)
; #define MFMA32(a, b, c) __builtin_amdgcn_mfma_f32_32x32x16_bf16((a), (b), (c), 0, 0, 0)
; DI void a_qkt(f32x16& p0, f32x16& p1, const char* Ks, const char* Ps, const bf16x8* qr, const char* QP, int r32, int hi) {
;     ...
;   for (int d0 = 0; d0 < 4; ++d0) { const int cb = (d0 * 16 + hi * 8) * 2;
;     bf16x8 b0 = *reinterpret_cast<const bf16x8*>(Ps + PSWZ(r32, cb));
;     bf16x8 b1 = *reinterpret_cast<const bf16x8*>(Ps + PSWZ(32 + r32, cb));
;     const bf16x8 qp = *reinterpret_cast<const bf16x8*>(QP + d0 * 1024);
;     p0 = MFMA32(b0, qp, p0);
;     p1 = MFMA32(b1, qp, p1); }
; DI void pv_sm(f32x16* o, int vb, bf16x8 pa0, bf16x8 pa1, bf16x8 pa2, bf16x8 pa3, f32x16& p0, f32x16& p1, float& m_reg, float& mn, float& alpha) {
;   PV_BLOCK(0)
;   float pm0 = p0[0];
; #pragma unroll
;   for (int r = 1; r < 16; ++r) pm0 = fmaxf(pm0, p0[r]);
;   PV_BLOCK(1)
;   float pmax = pm0;
; #pragma unroll
;   for (int r = 0; r < 16; ++r) pmax = fmaxf(pmax, p1[r]);
;   { auto rr = __builtin_amdgcn_permlane32_swap(__float_as_uint(pmax), __float_as_uint(pmax), false, false);
;     pmax = fmaxf(__uint_as_float(rr[0]), __uint_as_float(rr[1])); }
;   const bool keep = __all(pmax - m_reg <= ATH);
;   mn = keep ? m_reg : fmaxf(m_reg, pmax);
;   alpha = __builtin_amdgcn_exp2f(m_reg - mn);
;   m_reg = mn;
;   PV_BLOCK(2)
; #pragma unroll
;   for (int r = 0; r < 16; ++r) { p0[r] = p0[r] - mn; p1[r] = p1[r] - mn; }
;   PV_BLOCK(3)
; #pragma unroll
;   for (int r = 0; r < 16; ++r) p0[r] = __builtin_amdgcn_exp2f(p0[r]);
; }
	v_mfma_f32_32x32x16_bf16 v[66:81], v[220:223], v[102:105], v[66:81]
	v_add_u32_e32 v226, s9, v179
	ds_read_b128 v[216:219], v226 offset:32768
	ds_read_b128 v[220:223], v226 offset:36864
	ds_read_b128 v[228:231], v163
	v_add_f32_e32 v203, v157, v203
	v_add_f32_e32 v203, v184, v203
	v_cvt_pk_bf16_f32 v131, v242, v243
	s_waitcnt lgkmcnt(4)
	v_mfma_f32_32x32x16_bf16 v[82:97], v[204:207], v[98:101], v[82:97]
	v_add_f32_e32 v203, v185, v203
	v_add_f32_e32 v203, v192, v203
	v_cvt_pk_bf16_f32 v132, v244, v245
	s_waitcnt lgkmcnt(3)
	v_mfma_f32_32x32x16_bf16 v[66:81], v[208:211], v[98:101], v[66:81]
	v_add_u32_e32 v226, s9, v180
	ds_read_b128 v[204:207], v226 offset:32768
	ds_read_b128 v[208:211], v226 offset:36864
	ds_read_b128 v[234:237], v163 offset:1024
	v_add_f32_e32 v203, v193, v203
	v_add_f32_e32 v203, v194, v203
	v_cvt_pk_bf16_f32 v133, v246, v247
	s_waitcnt lgkmcnt(3)
	v_mfma_f32_32x32x16_bf16 v[82:97], v[216:219], v[228:231], v[82:97]
	v_add_f32_e32 v203, v195, v203
	v_add_f32_e32 v203, v196, v203
	v_cvt_pk_bf16_f32 v186, v248, v249
	v_mfma_f32_32x32x16_bf16 v[66:81], v[220:223], v[228:231], v[66:81]
	v_add_u32_e32 v226, s9, v181
	ds_read_b128 v[216:219], v226 offset:32768
	ds_read_b128 v[220:223], v226 offset:36864
	ds_read_b128 v[228:231], v163 offset:2048
	v_add_f32_e32 v203, v197, v203
	v_add_f32_e32 v203, v198, v203
	v_cvt_pk_bf16_f32 v187, v250, v251
	s_waitcnt lgkmcnt(3)
	v_mfma_f32_32x32x16_bf16 v[82:97], v[204:207], v[234:237], v[82:97]
	v_add_f32_e32 v203, v199, v203
	v_add_f32_e32 v203, v200, v203
	v_cvt_pk_bf16_f32 v188, v252, v253
	v_mfma_f32_32x32x16_bf16 v[66:81], v[208:211], v[234:237], v[66:81]
	v_add_u32_e32 v226, s9, v182
	ds_read_b128 v[204:207], v226 offset:32768
	ds_read_b128 v[208:211], v226 offset:36864
	ds_read_b128 v[234:237], v163 offset:3072
	v_add_f32_e32 v203, v201, v203
	v_add_f32_e32 v154, v202, v203
	v_cvt_pk_bf16_f32 v189, v254, v255
	s_waitcnt lgkmcnt(3)
	v_mfma_f32_32x32x16_bf16 v[82:97], v[216:219], v[228:231], v[82:97]
	v_mov_b32_e32 v155, v154
	v_cvt_pk_bf16_f32 v190, v144, v156
	v_cvt_pk_bf16_f32 v191, v157, v184
	v_permlane32_swap_b32_e32 v130, v132
	v_mfma_f32_32x32x16_bf16 v[66:81], v[220:223], v[228:231], v[66:81]
	v_add_u32_e32 v232, s7, v171
	ds_read_b64_tr_b16 v[214:215], v232 offset:0
	ds_read_b64_tr_b16 v[216:217], v232 offset:2048
	ds_read_b64_tr_b16 v[218:219], v232 offset:4096
	ds_read_b64_tr_b16 v[220:221], v232 offset:6144
	ds_read_b64_tr_b16 v[222:223], v232 offset:8192
	ds_read_b64_tr_b16 v[224:225], v232 offset:10240
	ds_read_b64_tr_b16 v[226:227], v232 offset:12288
	ds_read_b64_tr_b16 v[228:229], v232 offset:14336
	v_cvt_pk_bf16_f32 v192, v185, v192
	v_cvt_pk_bf16_f32 v193, v193, v194
	v_permlane32_swap_b32_e32 v154, v155
	v_permlane32_swap_b32_e32 v131, v133
	s_waitcnt lgkmcnt(8)
	v_mfma_f32_32x32x16_bf16 v[82:97], v[204:207], v[234:237], v[82:97]
	v_cvt_pk_bf16_f32 v194, v195, v196
	v_cvt_pk_bf16_f32 v195, v197, v198
	v_permlane32_swap_b32_e32 v186, v188
	v_mfma_f32_32x32x16_bf16 v[66:81], v[208:211], v[234:237], v[66:81]
	v_cvt_pk_bf16_f32 v196, v199, v200
	v_cvt_pk_bf16_f32 v197, v201, v202
	v_permlane32_swap_b32_e32 v187, v189
	s_nop 0
	v_permlane32_swap_b32_e32 v190, v192
	v_permlane32_swap_b32_e32 v191, v193
	v_permlane32_swap_b32_e32 v194, v196
	v_permlane32_swap_b32_e32 v195, v197
	s_waitcnt lgkmcnt(0)
	s_nop 0
	v_mfma_f32_32x32x16_bf16 v[2:17], v[130:133], v[214:217], v[2:17]
	v_add_co_u32_e32 v156, vcc, s59, v146
	s_nop 1
	v_addc_co_u32_e32 v157, vcc, 0, v147, vcc
	v_add_co_u32_e32 v146, vcc, s60, v146
	s_nop 1
	v_addc_co_u32_e32 v147, vcc, 0, v147, vcc
	global_load_dwordx4 v[198:201], v[156:157], off offset:256
	global_load_dwordx4 v[202:205], v[156:157], off
	global_load_dwordx4 v[206:209], v[146:147], off offset:256
	global_load_dwordx4 v[210:213], v[146:147], off
	v_add_co_u32_e32 v146, vcc, s61, v148
	s_nop 1
	v_addc_co_u32_e32 v147, vcc, 0, v149, vcc
	global_load_dwordx4 v[146:149], v[146:147], off
	v_add_u32_e32 v156, s7, v171
	ds_read_b64_tr_b16 v[214:215], v156 offset:0x200
	ds_read_b64_tr_b16 v[216:217], v156 offset:0xa00
	v_max_f32_e32 v144, v83, v83
	v_max_f32_e32 v157, v82, v82
	v_max_f32_e32 v144, v157, v144
	v_max3_f32 v144, v144, v84, v85
	v_max3_f32 v144, v144, v86, v87
	v_mfma_f32_32x32x16_bf16 v[2:17], v[186:189], v[218:221], v[2:17]
	ds_read_b64_tr_b16 v[218:219], v156 offset:0x1200
	ds_read_b64_tr_b16 v[220:221], v156 offset:0x1a00
	v_max3_f32 v144, v144, v88, v89
	v_max3_f32 v144, v144, v90, v91
	v_max3_f32 v144, v144, v92, v93
	v_max3_f32 v144, v144, v94, v95
	v_max3_f32 v144, v144, v96, v97
	v_mfma_f32_32x32x16_bf16 v[2:17], v[190:193], v[222:225], v[2:17]
	ds_read_b64_tr_b16 v[222:223], v156 offset:0x2200
	ds_read_b64_tr_b16 v[224:225], v156 offset:0x2a00
	ds_read_b64_tr_b16 v[230:231], v156 offset:0x3200
	ds_read_b64_tr_b16 v[232:233], v156 offset:0x3a00
	v_mfma_f32_32x32x16_bf16 v[2:17], v[194:197], v[226:229], v[2:17]
	s_waitcnt lgkmcnt(0)
; DI void pv_sm(f32x16* o, int vb, bf16x8 pa0, bf16x8 pa1, bf16x8 pa2, bf16x8 pa3, f32x16& p0, f32x16& p1, float& m_reg, float& mn, float& alpha) {
;   PV_BLOCK(0)
;   float pm0 = p0[0];
; #pragma unroll
;   for (int r = 1; r < 16; ++r) pm0 = fmaxf(pm0, p0[r]);
;   PV_BLOCK(1)
;   float pmax = pm0;
; #pragma unroll
;   for (int r = 0; r < 16; ++r) pmax = fmaxf(pmax, p1[r]);
;   { auto rr = __builtin_amdgcn_permlane32_swap(__float_as_uint(pmax), __float_as_uint(pmax), false, false);
;     pmax = fmaxf(__uint_as_float(rr[0]), __uint_as_float(rr[1])); }
;   const bool keep = __all(pmax - m_reg <= ATH);
;   mn = keep ? m_reg : fmaxf(m_reg, pmax);
;   alpha = __builtin_amdgcn_exp2f(m_reg - mn);
;   m_reg = mn;
;   PV_BLOCK(2)
; #pragma unroll
;   for (int r = 0; r < 16; ++r) { p0[r] = p0[r] - mn; p1[r] = p1[r] - mn; }
;   PV_BLOCK(3)
; #pragma unroll
;   for (int r = 0; r < 16; ++r) p0[r] = __builtin_amdgcn_exp2f(p0[r]);
; }
	v_mfma_f32_32x32x16_bf16 v[50:65], v[130:133], v[214:217], v[50:65]
	v_max3_f32 v144, v144, v66, v67
	v_max3_f32 v144, v144, v68, v69
	v_max3_f32 v144, v144, v70, v71
	v_max3_f32 v144, v144, v72, v73
	v_max3_f32 v144, v144, v74, v75
	v_max3_f32 v144, v144, v76, v77
	v_max3_f32 v144, v144, v78, v79
	v_mfma_f32_32x32x16_bf16 v[50:65], v[186:189], v[218:221], v[50:65]
	v_max3_f32 v144, v144, v80, v81
	v_mov_b32_e32 v157, v144
	s_nop 1
	v_permlane32_swap_b32_e32 v144, v157
	v_max_f32_e32 v157, v157, v157
	v_max_f32_e32 v144, v144, v144
	v_max_f32_e32 v144, v144, v157
	v_mfma_f32_32x32x16_bf16 v[50:65], v[190:193], v[222:225], v[50:65]
	ds_read_b64_tr_b16 v[214:215], v156 offset:0x400
	v_sub_f32_e32 v157, v144, v153
	ds_read_b64_tr_b16 v[216:217], v156 offset:0xc00
	v_cmp_ge_f32_e32 vcc, s54, v157
	ds_read_b64_tr_b16 v[218:219], v156 offset:0x1400
	s_cmp_eq_u64 vcc, exec
	v_max_f32_e32 v157, v153, v153
	ds_read_b64_tr_b16 v[220:221], v156 offset:0x1c00
	ds_read_b64_tr_b16 v[222:223], v156 offset:0x2400
	ds_read_b64_tr_b16 v[224:225], v156 offset:0x2c00
	ds_read_b64_tr_b16 v[226:227], v156 offset:0x3400
	ds_read_b64_tr_b16 v[228:229], v156 offset:0x3c00
	v_mfma_f32_32x32x16_bf16 v[50:65], v[194:197], v[230:233], v[50:65]
	v_max_f32_e32 v144, v157, v144
	s_cselect_b64 vcc, -1, 0
	v_cndmask_b32_e32 v144, v144, v153, vcc
	v_sub_f32_e32 v153, v153, v144
	v_exp_f32_e32 v184, v153
	s_waitcnt lgkmcnt(0)
	v_mfma_f32_32x32x16_bf16 v[34:49], v[130:133], v[214:217], v[34:49]
	ds_read_b64_tr_b16 v[214:215], v156 offset:0x600
	ds_read_b64_tr_b16 v[216:217], v156 offset:0xe00
	v_sub_f32_e32 v82, v82, v144
	v_sub_f32_e32 v83, v83, v144
	v_sub_f32_e32 v84, v84, v144
	v_sub_f32_e32 v85, v85, v144
	v_mfma_f32_32x32x16_bf16 v[34:49], v[186:189], v[218:221], v[34:49]
	ds_read_b64_tr_b16 v[218:219], v156 offset:0x1600
	ds_read_b64_tr_b16 v[220:221], v156 offset:0x1e00
	v_sub_f32_e32 v86, v86, v144
	v_sub_f32_e32 v87, v87, v144
	v_exp_f32_e32 v240, v82
	v_exp_f32_e32 v241, v83
	v_mfma_f32_32x32x16_bf16 v[34:49], v[190:193], v[222:225], v[34:49]
	ds_read_b64_tr_b16 v[222:223], v156 offset:0x2600
	ds_read_b64_tr_b16 v[224:225], v156 offset:0x2e00
	ds_read_b64_tr_b16 v[230:231], v156 offset:0x3600
	ds_read_b64_tr_b16 v[232:233], v156 offset:0x3e00
	v_mfma_f32_32x32x16_bf16 v[34:49], v[194:197], v[226:229], v[34:49]
	v_sub_f32_e32 v88, v88, v144
	v_sub_f32_e32 v89, v89, v144
	v_exp_f32_e32 v242, v84
	v_exp_f32_e32 v243, v85
	s_waitcnt lgkmcnt(0)
	v_sub_f32_e32 v90, v90, v144
	v_sub_f32_e32 v91, v91, v144
	v_exp_f32_e32 v244, v86
	v_exp_f32_e32 v245, v87
	v_mfma_f32_32x32x16_bf16 v[18:33], v[130:133], v[214:217], v[18:33]
	v_sub_f32_e32 v92, v92, v144
	v_sub_f32_e32 v93, v93, v144
	v_exp_f32_e32 v246, v88
	v_exp_f32_e32 v247, v89
	s_add_i32 s9, s8, 0
	v_add_u32_e32 v130, s9, v164
	s_waitcnt vmcnt(0)
	s_waitcnt vmcnt(4)
	ds_write_b128 v130, v[198:201]
	v_add_u32_e32 v130, s9, v165
	s_waitcnt vmcnt(2)
	ds_write_b128 v130, v[206:209]
	v_add_u32_e32 v130, s9, v167
	v_mfma_f32_32x32x16_bf16 v[18:33], v[186:189], v[218:221], v[18:33]
	ds_write_b128 v130, v[202:205] offset:16384
	v_add_u32_e32 v130, s9, v168
	s_waitcnt vmcnt(1)
	ds_write_b128 v130, v[210:213] offset:16384
	v_add_u32_e32 v130, s9, v169
	v_cmp_gt_f32_e32 vcc, 1.0, v184
	s_waitcnt vmcnt(0)
	ds_write_b128 v130, v[146:149] offset:32768
	v_sub_f32_e32 v94, v94, v144
	v_sub_f32_e32 v95, v95, v144
	v_exp_f32_e32 v248, v90
	v_exp_f32_e32 v249, v91
	v_mfma_f32_32x32x16_bf16 v[18:33], v[190:193], v[222:225], v[18:33]
	v_sub_f32_e32 v96, v96, v144
	v_sub_f32_e32 v97, v97, v144
	v_exp_f32_e32 v250, v92
	v_exp_f32_e32 v251, v93
	v_mfma_f32_32x32x16_bf16 v[18:33], v[194:197], v[230:233], v[18:33]
	v_exp_f32_e32 v252, v94
	v_exp_f32_e32 v253, v95
	v_exp_f32_e32 v254, v96
	v_exp_f32_e32 v255, v97
	s_cbranch_vccz .LBB0_673
	s_and_saveexec_b64 s[4:5], s[2:3]
	ds_write_b32 v161, v184 offset:128
	s_or_b64 exec, exec, s[4:5]
	s_waitcnt lgkmcnt(0)
	v_add_u32_e32 v153, v137, v134
	ds_read_b128 v[130:133], v153 offset:224
	ds_read_b128 v[146:149], v153 offset:192
	ds_read_b128 v[186:189], v153 offset:160
	ds_read_b128 v[190:193], v153 offset:128
	s_waitcnt lgkmcnt(3)
	v_pk_mul_f32 v[14:15], v[14:15], v[130:131]
	s_waitcnt lgkmcnt(2)
	v_pk_mul_f32 v[10:11], v[10:11], v[146:147]
	s_waitcnt lgkmcnt(1)
	v_pk_mul_f32 v[6:7], v[6:7], v[186:187]
	v_pk_mul_f32 v[16:17], v[16:17], v[132:133]
	v_pk_mul_f32 v[12:13], v[12:13], v[148:149]
	v_pk_mul_f32 v[8:9], v[8:9], v[188:189]
	s_waitcnt lgkmcnt(0)
	v_pk_mul_f32 v[4:5], v[4:5], v[192:193]
	v_pk_mul_f32 v[2:3], v[2:3], v[190:191]
	v_pk_mul_f32 v[62:63], v[62:63], v[130:131]
	v_pk_mul_f32 v[58:59], v[58:59], v[146:147]
	v_pk_mul_f32 v[54:55], v[54:55], v[186:187]
	v_pk_mul_f32 v[64:65], v[64:65], v[132:133]
	v_pk_mul_f32 v[60:61], v[60:61], v[148:149]
	v_pk_mul_f32 v[56:57], v[56:57], v[188:189]
	v_pk_mul_f32 v[52:53], v[52:53], v[192:193]
	v_pk_mul_f32 v[50:51], v[50:51], v[190:191]
	v_pk_mul_f32 v[46:47], v[46:47], v[130:131]
	v_pk_mul_f32 v[42:43], v[42:43], v[146:147]
	v_pk_mul_f32 v[38:39], v[38:39], v[186:187]
	v_pk_mul_f32 v[48:49], v[48:49], v[132:133]
	v_pk_mul_f32 v[44:45], v[44:45], v[148:149]
	v_pk_mul_f32 v[40:41], v[40:41], v[188:189]
	v_pk_mul_f32 v[36:37], v[36:37], v[192:193]
	v_pk_mul_f32 v[34:35], v[34:35], v[190:191]
	v_pk_mul_f32 v[30:31], v[30:31], v[130:131]
	v_pk_mul_f32 v[26:27], v[26:27], v[146:147]
	v_pk_mul_f32 v[22:23], v[22:23], v[186:187]
	v_pk_mul_f32 v[32:33], v[32:33], v[132:133]
	v_pk_mul_f32 v[28:29], v[28:29], v[148:149]
	v_pk_mul_f32 v[24:25], v[24:25], v[188:189]
	v_pk_mul_f32 v[20:21], v[20:21], v[192:193]
	v_pk_mul_f32 v[18:19], v[18:19], v[190:191]
